# GEMM unit headers: accumulator zeroing with 64 v_mov_b64 instead of 128 v_mov_b32 (6 GEMM instances)
# baseline (speedup 1.0000x reference)
;     __device__ bool next(int i, Unit& u) const { const int L = i * G + c; if (L >= ntot) return false; const int kc = L % nks, t = L / nks; u.pn = t % nN; u.pm = pm0 + t / nN; u.ko = kc * klen; return true; }
;     __device__ bool next(int i, Unit& u) const { const int L = i * G + c; if (L >= ntot) return false; u.pn = L % nN; u.pm = pm0 + L / nN; u.ko = 0; return true; }
;     __device__ bool next(int i, Unit& u) const { if (i >= nN) return false; int p = pm; asm volatile("" : "+s"(p)); u.pm = p; u.pn = i; u.ko = 0; return true; }
;     __device__ bool next(int i, Unit& u) const { if (i) return false; u.pm = pm; u.pn = pn; u.ko = 0; return true; }
; template <class Epi, class Sched, bool ALIGN_EPI = false, bool SP2 = false>
; __device__ __forceinline__ void gemm_phase(PG8_LAS unsigned char* lds, const Gemm g, const Sched& S, const Epi& E) {
;     ...
;         const bool has_next = S.next(ui + 1, nxt);
;         const char* nA = has_next ? (const char*)g.A + (size_t)nxt.pm * tstep + (size_t)nxt.ko * 2 : cA; const char* nB = has_next ? (const char*)g.Bt + (size_t)nxt.pn * tstep + (size_t)nxt.ko * 2 : cB;
;     ...
; #pragma unroll
;         for (int a = 0; a < 2; ++a)
; #pragma unroll
;             for (int b = 0; b < 2; ++b)
; #pragma unroll
;                 for (int m = 0; m < 4; ++m)
; #pragma unroll
;                     for (int n = 0; n < 2; ++n) acc[a][b][m][n] = (f32x4){0.f, 0.f, 0.f, 0.f};
;         cur = nxt; cA = nA; cB = nB; ++ui;
.LBB0_191:
	s_ashr_i32 s51, s50, 31
	s_lshl_b64 s[8:9], s[50:51], 19
	s_add_u32 s54, s47, s8
	s_addc_u32 s55, s71, s9
	s_and_b64 s[8:9], s[2:3], exec
	s_cselect_b32 s36, s55, s5
	s_cselect_b32 s37, s54, s4
	s_ashr_i32 s49, s48, 31
	s_lshl_b64 s[8:9], s[48:49], 19
	v_readlane_b32 s56, v254, 49
	v_readlane_b32 s57, v254, 50
	s_add_u32 s56, s56, s8
	s_addc_u32 s57, s57, s9
	s_and_b64 s[8:9], s[2:3], exec
	s_cselect_b32 s49, s57, s7
	s_cselect_b32 s51, s56, s6
	s_add_u32 s4, s4, 0x40080
	s_addc_u32 s5, s5, 0
	s_add_u32 s68, s6, 0x100
	v_mov_b64_e32 v[0:1], 0
	v_mov_b64_e32 v[2:3], 0
	v_mov_b64_e32 v[4:5], 0
	v_mov_b64_e32 v[6:7], 0
	v_mov_b64_e32 v[8:9], 0
	v_mov_b64_e32 v[10:11], 0
	v_mov_b64_e32 v[12:13], 0
	v_mov_b64_e32 v[14:15], 0
	v_mov_b64_e32 v[16:17], 0
	v_mov_b64_e32 v[18:19], 0
	v_mov_b64_e32 v[20:21], 0
	v_mov_b64_e32 v[22:23], 0
	v_mov_b64_e32 v[24:25], 0
	v_mov_b64_e32 v[26:27], 0
	v_mov_b64_e32 v[28:29], 0
	v_mov_b64_e32 v[30:31], 0
	v_mov_b64_e32 v[32:33], 0
	v_mov_b64_e32 v[34:35], 0
	v_mov_b64_e32 v[36:37], 0
	v_mov_b64_e32 v[38:39], 0
	v_mov_b64_e32 v[40:41], 0
	v_mov_b64_e32 v[42:43], 0
	v_mov_b64_e32 v[44:45], 0
	v_mov_b64_e32 v[46:47], 0
	v_mov_b64_e32 v[48:49], 0
	v_mov_b64_e32 v[50:51], 0
	v_mov_b64_e32 v[52:53], 0
	v_mov_b64_e32 v[54:55], 0
	v_mov_b64_e32 v[56:57], 0
	v_mov_b64_e32 v[58:59], 0
	v_mov_b64_e32 v[60:61], 0
	v_mov_b64_e32 v[62:63], 0
	v_mov_b64_e32 v[64:65], 0
	v_mov_b64_e32 v[66:67], 0
	v_mov_b64_e32 v[68:69], 0
	v_mov_b64_e32 v[70:71], 0
	v_mov_b64_e32 v[72:73], 0
	v_mov_b64_e32 v[74:75], 0
	v_mov_b64_e32 v[76:77], 0
	v_mov_b64_e32 v[78:79], 0
	v_mov_b64_e32 v[80:81], 0
	v_mov_b64_e32 v[82:83], 0
	v_mov_b64_e32 v[84:85], 0
	v_mov_b64_e32 v[86:87], 0
	v_mov_b64_e32 v[88:89], 0
	v_mov_b64_e32 v[90:91], 0
	v_mov_b64_e32 v[92:93], 0
	v_mov_b64_e32 v[94:95], 0
	v_mov_b64_e32 v[96:97], 0
	v_mov_b64_e32 v[98:99], 0
	v_mov_b64_e32 v[100:101], 0
	v_mov_b64_e32 v[102:103], 0
	v_mov_b64_e32 v[104:105], 0
	v_mov_b64_e32 v[106:107], 0
	v_mov_b64_e32 v[108:109], 0
	v_mov_b64_e32 v[110:111], 0
	v_mov_b64_e32 v[112:113], 0
	v_mov_b64_e32 v[114:115], 0
	v_mov_b64_e32 v[116:117], 0
	v_mov_b64_e32 v[118:119], 0
	v_mov_b64_e32 v[120:121], 0
	v_mov_b64_e32 v[122:123], 0
	v_mov_b64_e32 v[124:125], 0
	v_mov_b64_e32 v[126:127], 0
	s_addc_u32 s69, s7, 0
	s_mov_b32 s70, -2

;     __device__ bool next(int i, Unit& u) const { const int L = i * G + c; if (L >= ntot) return false; const int kc = L % nks, t = L / nks; u.pn = t % nN; u.pm = pm0 + t / nN; u.ko = kc * klen; return true; }
;     __device__ bool next(int i, Unit& u) const { const int L = i * G + c; if (L >= ntot) return false; u.pn = L % nN; u.pm = pm0 + L / nN; u.ko = 0; return true; }
;     __device__ bool next(int i, Unit& u) const { if (i >= nN) return false; int p = pm; asm volatile("" : "+s"(p)); u.pm = p; u.pn = i; u.ko = 0; return true; }
;     __device__ bool next(int i, Unit& u) const { if (i) return false; u.pm = pm; u.pn = pn; u.ko = 0; return true; }
; template <class Epi, class Sched, bool ALIGN_EPI = false, bool SP2 = false>
; __device__ __forceinline__ void gemm_phase(PG8_LAS unsigned char* lds, const Gemm g, const Sched& S, const Epi& E) {
;     ...
;         const bool has_next = S.next(ui + 1, nxt);
;         const char* nA = has_next ? (const char*)g.A + (size_t)nxt.pm * tstep + (size_t)nxt.ko * 2 : cA; const char* nB = has_next ? (const char*)g.Bt + (size_t)nxt.pn * tstep + (size_t)nxt.ko * 2 : cB;
;     ...
; #pragma unroll
;         for (int a = 0; a < 2; ++a)
; #pragma unroll
;             for (int b = 0; b < 2; ++b)
; #pragma unroll
;                 for (int m = 0; m < 4; ++m)
; #pragma unroll
;                     for (int n = 0; n < 2; ++n) acc[a][b][m][n] = (f32x4){0.f, 0.f, 0.f, 0.f};
;         cur = nxt; cA = nA; cB = nB; ++ui;
.LBB0_1539:
	s_ashr_i32 s19, s18, 31
	s_lshl_b64 s[22:23], s[18:19], 19
	s_add_u32 s19, s34, s22
	s_addc_u32 s21, s35, s23
	s_and_b64 s[22:23], s[24:25], exec
	s_cselect_b32 s23, s21, s27
	s_cselect_b32 s22, s19, s26
	s_ashr_i32 s21, s20, 31
	s_lshl_b64 s[30:31], s[20:21], 19
	s_add_u32 s19, s2, s30
	s_addc_u32 s21, s3, s31
	s_and_b64 s[24:25], s[24:25], exec
	s_cselect_b32 s25, s21, s29
	s_cselect_b32 s24, s19, s28
	s_add_u32 s26, s26, 0x40080
	s_addc_u32 s27, s27, 0
	s_add_u32 s19, s28, 0x100
	v_mov_b64_e32 v[0:1], 0
	v_mov_b64_e32 v[2:3], 0
	v_mov_b64_e32 v[4:5], 0
	v_mov_b64_e32 v[6:7], 0
	v_mov_b64_e32 v[8:9], 0
	v_mov_b64_e32 v[10:11], 0
	v_mov_b64_e32 v[12:13], 0
	v_mov_b64_e32 v[14:15], 0
	v_mov_b64_e32 v[16:17], 0
	v_mov_b64_e32 v[18:19], 0
	v_mov_b64_e32 v[20:21], 0
	v_mov_b64_e32 v[22:23], 0
	v_mov_b64_e32 v[24:25], 0
	v_mov_b64_e32 v[26:27], 0
	v_mov_b64_e32 v[28:29], 0
	v_mov_b64_e32 v[30:31], 0
	v_mov_b64_e32 v[32:33], 0
	v_mov_b64_e32 v[34:35], 0
	v_mov_b64_e32 v[36:37], 0
	v_mov_b64_e32 v[38:39], 0
	v_mov_b64_e32 v[40:41], 0
	v_mov_b64_e32 v[42:43], 0
	v_mov_b64_e32 v[44:45], 0
	v_mov_b64_e32 v[46:47], 0
	v_mov_b64_e32 v[48:49], 0
	v_mov_b64_e32 v[50:51], 0
	v_mov_b64_e32 v[52:53], 0
	v_mov_b64_e32 v[54:55], 0
	v_mov_b64_e32 v[56:57], 0
	v_mov_b64_e32 v[58:59], 0
	v_mov_b64_e32 v[60:61], 0
	v_mov_b64_e32 v[62:63], 0
	v_mov_b64_e32 v[64:65], 0
	v_mov_b64_e32 v[66:67], 0
	v_mov_b64_e32 v[68:69], 0
	v_mov_b64_e32 v[70:71], 0
	v_mov_b64_e32 v[72:73], 0
	v_mov_b64_e32 v[74:75], 0
	v_mov_b64_e32 v[76:77], 0
	v_mov_b64_e32 v[78:79], 0
	v_mov_b64_e32 v[80:81], 0
	v_mov_b64_e32 v[82:83], 0
	v_mov_b64_e32 v[84:85], 0
	v_mov_b64_e32 v[86:87], 0
	v_mov_b64_e32 v[88:89], 0
	v_mov_b64_e32 v[90:91], 0
	v_mov_b64_e32 v[92:93], 0
	v_mov_b64_e32 v[94:95], 0
	v_mov_b64_e32 v[96:97], 0
	v_mov_b64_e32 v[98:99], 0
	v_mov_b64_e32 v[100:101], 0
	v_mov_b64_e32 v[102:103], 0
	v_mov_b64_e32 v[104:105], 0
	v_mov_b64_e32 v[106:107], 0
	v_mov_b64_e32 v[108:109], 0
	v_mov_b64_e32 v[110:111], 0
	v_mov_b64_e32 v[112:113], 0
	v_mov_b64_e32 v[114:115], 0
	v_mov_b64_e32 v[116:117], 0
	v_mov_b64_e32 v[118:119], 0
	v_mov_b64_e32 v[120:121], 0
	v_mov_b64_e32 v[122:123], 0
	v_mov_b64_e32 v[124:125], 0
	v_mov_b64_e32 v[126:127], 0
	s_addc_u32 s21, s29, 0
	s_mov_b32 s48, -2

;     __device__ bool next(int i, Unit& u) const { const int L = i * G + c; if (L >= ntot) return false; const int kc = L % nks, t = L / nks; u.pn = t % nN; u.pm = pm0 + t / nN; u.ko = kc * klen; return true; }
;     __device__ bool next(int i, Unit& u) const { const int L = i * G + c; if (L >= ntot) return false; u.pn = L % nN; u.pm = pm0 + L / nN; u.ko = 0; return true; }
;     __device__ bool next(int i, Unit& u) const { if (i >= nN) return false; int p = pm; asm volatile("" : "+s"(p)); u.pm = p; u.pn = i; u.ko = 0; return true; }
;     __device__ bool next(int i, Unit& u) const { if (i) return false; u.pm = pm; u.pn = pn; u.ko = 0; return true; }
; template <class Epi, class Sched, bool ALIGN_EPI = false, bool SP2 = false>
; __device__ __forceinline__ void gemm_phase(PG8_LAS unsigned char* lds, const Gemm g, const Sched& S, const Epi& E) {
;     ...
;         const bool has_next = S.next(ui + 1, nxt);
;         const char* nA = has_next ? (const char*)g.A + (size_t)nxt.pm * tstep + (size_t)nxt.ko * 2 : cA; const char* nB = has_next ? (const char*)g.Bt + (size_t)nxt.pn * tstep + (size_t)nxt.ko * 2 : cB;
;     ...
; #pragma unroll
;         for (int a = 0; a < 2; ++a)
; #pragma unroll
;             for (int b = 0; b < 2; ++b)
; #pragma unroll
;                 for (int m = 0; m < 4; ++m)
; #pragma unroll
;                     for (int n = 0; n < 2; ++n) acc[a][b][m][n] = (f32x4){0.f, 0.f, 0.f, 0.f};
;         cur = nxt; cA = nA; cB = nB; ++ui;
.LBB0_1603:
	s_ashr_i32 s21, s20, 31
	s_lshl_b64 s[24:25], s[20:21], 19
	s_add_u32 s24, s10, s24
	s_addc_u32 s25, s11, s25
	s_and_b64 s[26:27], s[34:35], exec
	s_cselect_b32 s21, s25, s31
	s_cselect_b32 s45, s24, s30
	s_ashr_i32 s23, s22, 31
	s_lshl_b64 s[26:27], s[22:23], 19
	s_add_u32 s26, s4, s26
	s_addc_u32 s27, s5, s27
	s_and_b64 s[34:35], s[34:35], exec
	s_cselect_b32 s23, s27, s37
	s_cselect_b32 s46, s26, s36
	s_add_u32 s30, s30, 0x40080
	s_addc_u32 s31, s31, 0
	s_add_u32 s47, s36, 0x100
	v_mov_b64_e32 v[0:1], 0
	v_mov_b64_e32 v[2:3], 0
	v_mov_b64_e32 v[4:5], 0
	v_mov_b64_e32 v[6:7], 0
	v_mov_b64_e32 v[8:9], 0
	v_mov_b64_e32 v[10:11], 0
	v_mov_b64_e32 v[12:13], 0
	v_mov_b64_e32 v[14:15], 0
	v_mov_b64_e32 v[16:17], 0
	v_mov_b64_e32 v[18:19], 0
	v_mov_b64_e32 v[20:21], 0
	v_mov_b64_e32 v[22:23], 0
	v_mov_b64_e32 v[24:25], 0
	v_mov_b64_e32 v[26:27], 0
	v_mov_b64_e32 v[28:29], 0
	v_mov_b64_e32 v[30:31], 0
	v_mov_b64_e32 v[32:33], 0
	v_mov_b64_e32 v[34:35], 0
	v_mov_b64_e32 v[36:37], 0
	v_mov_b64_e32 v[38:39], 0
	v_mov_b64_e32 v[40:41], 0
	v_mov_b64_e32 v[42:43], 0
	v_mov_b64_e32 v[44:45], 0
	v_mov_b64_e32 v[46:47], 0
	v_mov_b64_e32 v[48:49], 0
	v_mov_b64_e32 v[50:51], 0
	v_mov_b64_e32 v[52:53], 0
	v_mov_b64_e32 v[54:55], 0
	v_mov_b64_e32 v[56:57], 0
	v_mov_b64_e32 v[58:59], 0
	v_mov_b64_e32 v[60:61], 0
	v_mov_b64_e32 v[62:63], 0
	v_mov_b64_e32 v[64:65], 0
	v_mov_b64_e32 v[66:67], 0
	v_mov_b64_e32 v[68:69], 0
	v_mov_b64_e32 v[70:71], 0
	v_mov_b64_e32 v[72:73], 0
	v_mov_b64_e32 v[74:75], 0
	v_mov_b64_e32 v[76:77], 0
	v_mov_b64_e32 v[78:79], 0
	v_mov_b64_e32 v[80:81], 0
	v_mov_b64_e32 v[82:83], 0
	v_mov_b64_e32 v[84:85], 0
	v_mov_b64_e32 v[86:87], 0
	v_mov_b64_e32 v[88:89], 0
	v_mov_b64_e32 v[90:91], 0
	v_mov_b64_e32 v[92:93], 0
	v_mov_b64_e32 v[94:95], 0
	v_mov_b64_e32 v[96:97], 0
	v_mov_b64_e32 v[98:99], 0
	v_mov_b64_e32 v[100:101], 0
	v_mov_b64_e32 v[102:103], 0
	v_mov_b64_e32 v[104:105], 0
	v_mov_b64_e32 v[106:107], 0
	v_mov_b64_e32 v[108:109], 0
	v_mov_b64_e32 v[110:111], 0
	v_mov_b64_e32 v[112:113], 0
	v_mov_b64_e32 v[114:115], 0
	v_mov_b64_e32 v[116:117], 0
	v_mov_b64_e32 v[118:119], 0
	v_mov_b64_e32 v[120:121], 0
	v_mov_b64_e32 v[122:123], 0
	v_mov_b64_e32 v[124:125], 0
	v_mov_b64_e32 v[126:127], 0
	s_addc_u32 s48, s37, 0
	s_mov_b32 s49, -2

;     __device__ bool next(int i, Unit& u) const { const int L = i * G + c; if (L >= ntot) return false; const int kc = L % nks, t = L / nks; u.pn = t % nN; u.pm = pm0 + t / nN; u.ko = kc * klen; return true; }
;     __device__ bool next(int i, Unit& u) const { const int L = i * G + c; if (L >= ntot) return false; u.pn = L % nN; u.pm = pm0 + L / nN; u.ko = 0; return true; }
;     __device__ bool next(int i, Unit& u) const { if (i >= nN) return false; int p = pm; asm volatile("" : "+s"(p)); u.pm = p; u.pn = i; u.ko = 0; return true; }
;     __device__ bool next(int i, Unit& u) const { if (i) return false; u.pm = pm; u.pn = pn; u.ko = 0; return true; }
; template <class Epi, class Sched, bool ALIGN_EPI = false, bool SP2 = false>
; __device__ __forceinline__ void gemm_phase(PG8_LAS unsigned char* lds, const Gemm g, const Sched& S, const Epi& E) {
;     ...
;         const bool has_next = S.next(ui + 1, nxt);
;         const char* nA = has_next ? (const char*)g.A + (size_t)nxt.pm * tstep + (size_t)nxt.ko * 2 : cA; const char* nB = has_next ? (const char*)g.Bt + (size_t)nxt.pn * tstep + (size_t)nxt.ko * 2 : cB;
;     ...
; #pragma unroll
;         for (int a = 0; a < 2; ++a)
; #pragma unroll
;             for (int b = 0; b < 2; ++b)
; #pragma unroll
;                 for (int m = 0; m < 4; ++m)
; #pragma unroll
;                     for (int n = 0; n < 2; ++n) acc[a][b][m][n] = (f32x4){0.f, 0.f, 0.f, 0.f};
;         cur = nxt; cA = nA; cB = nB; ++ui;
.LBB0_1629:
	s_ashr_i32 s25, s24, 31
	s_lshl_b64 s[28:29], s[24:25], 18
	s_add_u32 s25, s14, s28
	s_addc_u32 s27, s15, s29
	s_and_b64 s[28:29], s[30:31], exec
	s_cselect_b32 s29, s27, s35
	s_cselect_b32 s28, s25, s34
	s_ashr_i32 s27, s26, 31
	s_lshl_b64 s[38:39], s[26:27], 18
	s_add_u32 s25, s4, s38
	s_addc_u32 s27, s5, s39
	s_and_b64 s[30:31], s[30:31], exec
	s_cselect_b32 s31, s27, s37
	s_cselect_b32 s30, s25, s36
	s_add_u32 s34, s34, 0x20080
	s_addc_u32 s35, s35, 0
	s_add_u32 s25, s36, 0x100
	v_mov_b64_e32 v[0:1], 0
	v_mov_b64_e32 v[2:3], 0
	v_mov_b64_e32 v[4:5], 0
	v_mov_b64_e32 v[6:7], 0
	v_mov_b64_e32 v[8:9], 0
	v_mov_b64_e32 v[10:11], 0
	v_mov_b64_e32 v[12:13], 0
	v_mov_b64_e32 v[14:15], 0
	v_mov_b64_e32 v[16:17], 0
	v_mov_b64_e32 v[18:19], 0
	v_mov_b64_e32 v[20:21], 0
	v_mov_b64_e32 v[22:23], 0
	v_mov_b64_e32 v[24:25], 0
	v_mov_b64_e32 v[26:27], 0
	v_mov_b64_e32 v[28:29], 0
	v_mov_b64_e32 v[30:31], 0
	v_mov_b64_e32 v[32:33], 0
	v_mov_b64_e32 v[34:35], 0
	v_mov_b64_e32 v[36:37], 0
	v_mov_b64_e32 v[38:39], 0
	v_mov_b64_e32 v[40:41], 0
	v_mov_b64_e32 v[42:43], 0
	v_mov_b64_e32 v[44:45], 0
	v_mov_b64_e32 v[46:47], 0
	v_mov_b64_e32 v[48:49], 0
	v_mov_b64_e32 v[50:51], 0
	v_mov_b64_e32 v[52:53], 0
	v_mov_b64_e32 v[54:55], 0
	v_mov_b64_e32 v[56:57], 0
	v_mov_b64_e32 v[58:59], 0
	v_mov_b64_e32 v[60:61], 0
	v_mov_b64_e32 v[62:63], 0
	v_mov_b64_e32 v[64:65], 0
	v_mov_b64_e32 v[66:67], 0
	v_mov_b64_e32 v[68:69], 0
	v_mov_b64_e32 v[70:71], 0
	v_mov_b64_e32 v[72:73], 0
	v_mov_b64_e32 v[74:75], 0
	v_mov_b64_e32 v[76:77], 0
	v_mov_b64_e32 v[78:79], 0
	v_mov_b64_e32 v[80:81], 0
	v_mov_b64_e32 v[82:83], 0
	v_mov_b64_e32 v[84:85], 0
	v_mov_b64_e32 v[86:87], 0
	v_mov_b64_e32 v[88:89], 0
	v_mov_b64_e32 v[90:91], 0
	v_mov_b64_e32 v[92:93], 0
	v_mov_b64_e32 v[94:95], 0
	v_mov_b64_e32 v[96:97], 0
	v_mov_b64_e32 v[98:99], 0
	v_mov_b64_e32 v[100:101], 0
	v_mov_b64_e32 v[102:103], 0
	v_mov_b64_e32 v[104:105], 0
	v_mov_b64_e32 v[106:107], 0
	v_mov_b64_e32 v[108:109], 0
	v_mov_b64_e32 v[110:111], 0
	v_mov_b64_e32 v[112:113], 0
	v_mov_b64_e32 v[114:115], 0
	v_mov_b64_e32 v[116:117], 0
	v_mov_b64_e32 v[118:119], 0
	v_mov_b64_e32 v[120:121], 0
	v_mov_b64_e32 v[122:123], 0
	v_mov_b64_e32 v[124:125], 0
	v_mov_b64_e32 v[126:127], 0
	s_addc_u32 s27, s37, 0
	s_mov_b32 s56, -2

;     __device__ bool next(int i, Unit& u) const { const int L = i * G + c; if (L >= ntot) return false; const int kc = L % nks, t = L / nks; u.pn = t % nN; u.pm = pm0 + t / nN; u.ko = kc * klen; return true; }
;     __device__ bool next(int i, Unit& u) const { const int L = i * G + c; if (L >= ntot) return false; u.pn = L % nN; u.pm = pm0 + L / nN; u.ko = 0; return true; }
;     __device__ bool next(int i, Unit& u) const { if (i >= nN) return false; int p = pm; asm volatile("" : "+s"(p)); u.pm = p; u.pn = i; u.ko = 0; return true; }
;     __device__ bool next(int i, Unit& u) const { if (i) return false; u.pm = pm; u.pn = pn; u.ko = 0; return true; }
; template <class Epi, class Sched, bool ALIGN_EPI = false, bool SP2 = false>
; __device__ __forceinline__ void gemm_phase(PG8_LAS unsigned char* lds, const Gemm g, const Sched& S, const Epi& E) {
;     ...
;         const bool has_next = S.next(ui + 1, nxt);
;         const char* nA = has_next ? (const char*)g.A + (size_t)nxt.pm * tstep + (size_t)nxt.ko * 2 : cA; const char* nB = has_next ? (const char*)g.Bt + (size_t)nxt.pn * tstep + (size_t)nxt.ko * 2 : cB;
;     ...
; #pragma unroll
;         for (int a = 0; a < 2; ++a)
; #pragma unroll
;             for (int b = 0; b < 2; ++b)
; #pragma unroll
;                 for (int m = 0; m < 4; ++m)
; #pragma unroll
;                     for (int n = 0; n < 2; ++n) acc[a][b][m][n] = (f32x4){0.f, 0.f, 0.f, 0.f};
;         cur = nxt; cA = nA; cB = nB; ++ui;
; __global__ void __launch_bounds__(512, 2) mk_fwd(Params P) {
;     ...
;         pg8::Gemm g{(const bf16_t*)(ws + WS_R2), (const bf16_t*)(ws + WS_WUP), MP, DFF, DM, DM}; pg8::StaticOrder S; S.init(MP, DFF, G, (int)blockIdx.x);
;         pg8::EpiScale<1> E{(bf16_t*)(ws + WS_H), DFF, (const float*)(ws + WS_SSQ), 1.0f};
;         pg8::gemm_phase<pg8::EpiScale<1>, pg8::StaticOrder, true, true>(lds, g, S, E);
.LBB0_1716:
	s_ashr_i32 s17, s16, 31
	s_lshl_b64 s[18:19], s[16:17], 19
	s_add_u32 s18, s31, s18
	s_addc_u32 s19, s33, s19
	s_and_b64 s[20:21], s[0:1], exec
	s_cselect_b32 s17, s19, s25
	s_cselect_b32 s47, s18, s24
	s_ashr_i32 s15, s14, 31
	s_lshl_b64 s[20:21], s[14:15], 19
	s_add_u32 s20, s34, s20
	s_addc_u32 s21, s35, s21
	s_and_b64 s[28:29], s[0:1], exec
	s_cselect_b32 s15, s21, s27
	s_cselect_b32 s48, s20, s26
	s_add_u32 s24, s24, 0x40080
	s_addc_u32 s25, s25, 0
	s_add_u32 s49, s26, 0x100
	v_mov_b64_e32 v[0:1], 0
	v_mov_b64_e32 v[2:3], 0
	v_mov_b64_e32 v[4:5], 0
	v_mov_b64_e32 v[6:7], 0
	v_mov_b64_e32 v[8:9], 0
	v_mov_b64_e32 v[10:11], 0
	v_mov_b64_e32 v[12:13], 0
	v_mov_b64_e32 v[14:15], 0
	v_mov_b64_e32 v[16:17], 0
	v_mov_b64_e32 v[18:19], 0
	v_mov_b64_e32 v[20:21], 0
	v_mov_b64_e32 v[22:23], 0
	v_mov_b64_e32 v[24:25], 0
	v_mov_b64_e32 v[26:27], 0
	v_mov_b64_e32 v[28:29], 0
	v_mov_b64_e32 v[30:31], 0
	v_mov_b64_e32 v[32:33], 0
	v_mov_b64_e32 v[34:35], 0
	v_mov_b64_e32 v[36:37], 0
	v_mov_b64_e32 v[38:39], 0
	v_mov_b64_e32 v[40:41], 0
	v_mov_b64_e32 v[42:43], 0
	v_mov_b64_e32 v[44:45], 0
	v_mov_b64_e32 v[46:47], 0
	v_mov_b64_e32 v[48:49], 0
	v_mov_b64_e32 v[50:51], 0
	v_mov_b64_e32 v[52:53], 0
	v_mov_b64_e32 v[54:55], 0
	v_mov_b64_e32 v[56:57], 0
	v_mov_b64_e32 v[58:59], 0
	v_mov_b64_e32 v[60:61], 0
	v_mov_b64_e32 v[62:63], 0
	v_mov_b64_e32 v[64:65], 0
	v_mov_b64_e32 v[66:67], 0
	v_mov_b64_e32 v[68:69], 0
	v_mov_b64_e32 v[70:71], 0
	v_mov_b64_e32 v[72:73], 0
	v_mov_b64_e32 v[74:75], 0
	v_mov_b64_e32 v[76:77], 0
	v_mov_b64_e32 v[78:79], 0
	v_mov_b64_e32 v[80:81], 0
	v_mov_b64_e32 v[82:83], 0
	v_mov_b64_e32 v[84:85], 0
	v_mov_b64_e32 v[86:87], 0
	v_mov_b64_e32 v[88:89], 0
	v_mov_b64_e32 v[90:91], 0
	v_mov_b64_e32 v[92:93], 0
	v_mov_b64_e32 v[94:95], 0
	v_mov_b64_e32 v[96:97], 0
	v_mov_b64_e32 v[98:99], 0
	v_mov_b64_e32 v[100:101], 0
	v_mov_b64_e32 v[102:103], 0
	v_mov_b64_e32 v[104:105], 0
	v_mov_b64_e32 v[106:107], 0
	v_mov_b64_e32 v[108:109], 0
	v_mov_b64_e32 v[110:111], 0
	v_mov_b64_e32 v[112:113], 0
	v_mov_b64_e32 v[114:115], 0
	v_mov_b64_e32 v[116:117], 0
	v_mov_b64_e32 v[118:119], 0
	v_mov_b64_e32 v[120:121], 0
	v_mov_b64_e32 v[122:123], 0
	v_mov_b64_e32 v[124:125], 0
	v_mov_b64_e32 v[126:127], 0
	s_addc_u32 s50, s27, 0
	s_mov_b32 s51, -2

;     __device__ bool next(int i, Unit& u) const { const int L = i * G + c; if (L >= ntot) return false; const int kc = L % nks, t = L / nks; u.pn = t % nN; u.pm = pm0 + t / nN; u.ko = kc * klen; return true; }
;     __device__ bool next(int i, Unit& u) const { const int L = i * G + c; if (L >= ntot) return false; u.pn = L % nN; u.pm = pm0 + L / nN; u.ko = 0; return true; }
;     __device__ bool next(int i, Unit& u) const { if (i >= nN) return false; int p = pm; asm volatile("" : "+s"(p)); u.pm = p; u.pn = i; u.ko = 0; return true; }
;     __device__ bool next(int i, Unit& u) const { if (i) return false; u.pm = pm; u.pn = pn; u.ko = 0; return true; }
; template <class Epi, class Sched, bool ALIGN_EPI = false, bool SP2 = false>
; __device__ __forceinline__ void gemm_phase(PG8_LAS unsigned char* lds, const Gemm g, const Sched& S, const Epi& E) {
;     ...
;         const bool has_next = S.next(ui + 1, nxt);
;         const char* nA = has_next ? (const char*)g.A + (size_t)nxt.pm * tstep + (size_t)nxt.ko * 2 : cA; const char* nB = has_next ? (const char*)g.Bt + (size_t)nxt.pn * tstep + (size_t)nxt.ko * 2 : cB;
;     ...
; #pragma unroll
;         for (int a = 0; a < 2; ++a)
; #pragma unroll
;             for (int b = 0; b < 2; ++b)
; #pragma unroll
;                 for (int m = 0; m < 4; ++m)
; #pragma unroll
;                     for (int n = 0; n < 2; ++n) acc[a][b][m][n] = (f32x4){0.f, 0.f, 0.f, 0.f};
;         cur = nxt; cA = nA; cB = nB; ++ui;
; __global__ void __launch_bounds__(512, 2) mk_fwd(Params P) {
;     ...
;         pg8::Gemm g{(const bf16_t*)(ws + WS_H), (const bf16_t*)(ws + WS_WDN), MP, DM, DFF, DFF}; pg8::StaticOrder S; S.init(MP, DM, G, (int)blockIdx.x);
;         pg8::EpiRes E{P.out + O_Y, P.out + O_Y + (size_t)MP * DM, P.out + O_Y, nullptr, nullptr};
;         pg8::gemm_phase<pg8::EpiRes, pg8::StaticOrder, true, true>(lds, g, S, E);
.LBB0_1755:
	s_ashr_i32 s15, s14, 31
	s_lshl_b64 s[16:17], s[14:15], 21
	s_add_u32 s16, s30, s16
	s_addc_u32 s17, s31, s17
	s_and_b64 s[18:19], s[0:1], exec
	s_cselect_b32 s15, s17, s25
	s_cselect_b32 s21, s16, s24
	s_ashr_i32 s13, s12, 31
	s_lshl_b64 s[18:19], s[12:13], 21
	s_add_u32 s18, s33, s18
	s_addc_u32 s19, s34, s19
	s_and_b64 s[28:29], s[0:1], exec
	s_cselect_b32 s13, s19, s27
	s_cselect_b32 s23, s18, s26
	s_add_u32 s24, s24, 0x100080
	s_addc_u32 s25, s25, 0
	s_add_u32 s48, s26, 0x100
	v_mov_b64_e32 v[0:1], 0
	v_mov_b64_e32 v[2:3], 0
	v_mov_b64_e32 v[4:5], 0
	v_mov_b64_e32 v[6:7], 0
	v_mov_b64_e32 v[8:9], 0
	v_mov_b64_e32 v[10:11], 0
	v_mov_b64_e32 v[12:13], 0
	v_mov_b64_e32 v[14:15], 0
	v_mov_b64_e32 v[16:17], 0
	v_mov_b64_e32 v[18:19], 0
	v_mov_b64_e32 v[20:21], 0
	v_mov_b64_e32 v[22:23], 0
	v_mov_b64_e32 v[24:25], 0
	v_mov_b64_e32 v[26:27], 0
	v_mov_b64_e32 v[28:29], 0
	v_mov_b64_e32 v[30:31], 0
	v_mov_b64_e32 v[32:33], 0
	v_mov_b64_e32 v[34:35], 0
	v_mov_b64_e32 v[36:37], 0
	v_mov_b64_e32 v[38:39], 0
	v_mov_b64_e32 v[40:41], 0
	v_mov_b64_e32 v[42:43], 0
	v_mov_b64_e32 v[44:45], 0
	v_mov_b64_e32 v[46:47], 0
	v_mov_b64_e32 v[48:49], 0
	v_mov_b64_e32 v[50:51], 0
	v_mov_b64_e32 v[52:53], 0
	v_mov_b64_e32 v[54:55], 0
	v_mov_b64_e32 v[56:57], 0
	v_mov_b64_e32 v[58:59], 0
	v_mov_b64_e32 v[60:61], 0
	v_mov_b64_e32 v[62:63], 0
	v_mov_b64_e32 v[64:65], 0
	v_mov_b64_e32 v[66:67], 0
	v_mov_b64_e32 v[68:69], 0
	v_mov_b64_e32 v[70:71], 0
	v_mov_b64_e32 v[72:73], 0
	v_mov_b64_e32 v[74:75], 0
	v_mov_b64_e32 v[76:77], 0
	v_mov_b64_e32 v[78:79], 0
	v_mov_b64_e32 v[80:81], 0
	v_mov_b64_e32 v[82:83], 0
	v_mov_b64_e32 v[84:85], 0
	v_mov_b64_e32 v[86:87], 0
	v_mov_b64_e32 v[88:89], 0
	v_mov_b64_e32 v[90:91], 0
	v_mov_b64_e32 v[92:93], 0
	v_mov_b64_e32 v[94:95], 0
	v_mov_b64_e32 v[96:97], 0
	v_mov_b64_e32 v[98:99], 0
	v_mov_b64_e32 v[100:101], 0
	v_mov_b64_e32 v[102:103], 0
	v_mov_b64_e32 v[104:105], 0
	v_mov_b64_e32 v[106:107], 0
	v_mov_b64_e32 v[108:109], 0
	v_mov_b64_e32 v[110:111], 0
	v_mov_b64_e32 v[112:113], 0
	v_mov_b64_e32 v[114:115], 0
	v_mov_b64_e32 v[116:117], 0
	v_mov_b64_e32 v[118:119], 0
	v_mov_b64_e32 v[120:121], 0
	v_mov_b64_e32 v[122:123], 0
	v_mov_b64_e32 v[124:125], 0
	v_mov_b64_e32 v[126:127], 0
	s_addc_u32 s49, s27, 0
	s_mov_b32 s50, -2
